# attention key-block loops: 4 K-fragment ds_reads issued up front (counted lgkmcnt), cross-half max via v_permlane32_swap instead of ds_bpermute
# baseline (speedup 1.0000x reference)
.LBB0_165:
	v_add_u32_e32 v100, 0, v92
	ds_read_b128 v[34:37], v100
	ds_read_b128 v[96:99], v100 offset:32
	ds_read_b128 v[144:147], v100 offset:64
	ds_read_b128 v[148:151], v100 offset:96
	s_waitcnt lgkmcnt(3)
	v_mfma_f32_32x32x16_bf16 v[34:49], v[34:37], v[50:53], 0
	s_waitcnt lgkmcnt(2)
	v_mfma_f32_32x32x16_bf16 v[34:49], v[96:99], v[54:57], v[34:49]
	s_waitcnt lgkmcnt(1)
	v_mfma_f32_32x32x16_bf16 v[34:49], v[144:147], v[58:61], v[34:49]
	s_waitcnt lgkmcnt(0)
	v_mfma_f32_32x32x16_bf16 v[34:49], v[148:151], v[62:65], v[34:49]
	v_add_u32_e32 v98, 0x19b94, v90
	ds_read_b32 v112, v98 offset:108
	ds_read_b32 v113, v98 offset:104
	ds_read_b32 v114, v98 offset:100
	ds_read_b32 v115, v98 offset:96
	ds_read_b32 v116, v98 offset:76
	ds_read_b32 v117, v98 offset:72
	ds_read_b32 v118, v98 offset:68
	ds_read_b32 v119, v98 offset:64
	ds_read_b32 v120, v98 offset:44
	ds_read_b32 v121, v98 offset:40
	ds_read_b32 v122, v98 offset:36
	ds_read_b32 v123, v98 offset:32
	ds_read_b32 v124, v98 offset:12
	ds_read_b32 v125, v98 offset:8
	ds_read_b32 v126, v98 offset:4
	ds_read_b32 v127, v98
	v_mov_b32_e32 v128, 0xf149f2ca
	v_add_u32_e32 v129, 27, v91
	s_waitcnt lgkmcnt(0)
	v_cmp_gt_u32_e32 vcc, s49, v129
	v_add_f32_e32 v112, v34, v112
	v_add_u32_e32 v129, 26, v91
	v_cndmask_b32_e32 v97, v128, v112, vcc
	v_cmp_gt_u32_e32 vcc, s49, v129
	v_add_f32_e32 v113, v35, v113
	v_add_u32_e32 v129, 25, v91
	v_cndmask_b32_e32 v96, v128, v113, vcc
	v_cmp_gt_u32_e32 vcc, s49, v129
	v_add_f32_e32 v114, v36, v114
	v_add_u32_e32 v129, 24, v91
	v_cndmask_b32_e32 v99, v128, v114, vcc
	v_cmp_gt_u32_e32 vcc, s49, v129
	v_add_f32_e32 v115, v37, v115
	v_add_u32_e32 v129, 19, v91
	v_cndmask_b32_e32 v35, v128, v115, vcc
	v_cmp_gt_u32_e32 vcc, s49, v129
	v_add_f32_e32 v116, v38, v116
	v_add_u32_e32 v129, 18, v91
	v_cndmask_b32_e32 v37, v128, v116, vcc
	v_cmp_gt_u32_e32 vcc, s49, v129
	v_add_f32_e32 v117, v39, v117
	v_add_u32_e32 v129, 17, v91
	v_cndmask_b32_e32 v36, v128, v117, vcc
	v_cmp_gt_u32_e32 vcc, s49, v129
	v_add_f32_e32 v118, v40, v118
	v_add_u32_e32 v129, 16, v91
	v_cndmask_b32_e32 v100, v128, v118, vcc
	v_cmp_gt_u32_e32 vcc, s49, v129
	v_add_f32_e32 v119, v41, v119
	v_add_u32_e32 v129, 11, v91
	v_cndmask_b32_e32 v39, v128, v119, vcc
	v_cmp_gt_u32_e32 vcc, s49, v129
	v_add_f32_e32 v120, v42, v120
	v_add_u32_e32 v129, 10, v91
	v_cndmask_b32_e32 v41, v128, v120, vcc
	v_cmp_gt_u32_e32 vcc, s49, v129
	v_add_f32_e32 v121, v43, v121
	v_add_u32_e32 v129, 9, v91
	v_cndmask_b32_e32 v40, v128, v121, vcc
	v_cmp_gt_u32_e32 vcc, s49, v129
	v_add_f32_e32 v122, v44, v122
	v_add_u32_e32 v129, 8, v91
	v_cndmask_b32_e32 v43, v128, v122, vcc
	v_cmp_gt_u32_e32 vcc, s49, v129
	v_add_f32_e32 v123, v45, v123
	v_add_u32_e32 v129, 3, v91
	v_cndmask_b32_e32 v42, v128, v123, vcc
	v_cmp_gt_u32_e32 vcc, s49, v129
	v_add_f32_e32 v124, v46, v124
	v_add_u32_e32 v129, 2, v91
	v_cndmask_b32_e32 v45, v128, v124, vcc
	v_cmp_gt_u32_e32 vcc, s49, v129
	v_add_f32_e32 v125, v47, v125
	v_add_u32_e32 v129, 1, v91
	v_cndmask_b32_e32 v44, v128, v125, vcc
	v_cmp_gt_u32_e32 vcc, s49, v129
	v_add_f32_e32 v126, v48, v126
	v_mov_b32_e32 v129, v91
	v_cndmask_b32_e32 v46, v128, v126, vcc
	v_cmp_gt_u32_e32 vcc, s49, v129
	v_add_f32_e32 v127, v49, v127
	s_nop 0
	v_cndmask_b32_e32 v38, v128, v127, vcc
	v_max_f32_e32 v34, v96, v96
	v_max_f32_e32 v47, v97, v97
	v_max_f32_e32 v34, v47, v34
	v_max3_f32 v34, v34, v99, v35
	v_max3_f32 v34, v34, v37, v36
	v_max3_f32 v34, v34, v100, v39
	v_max3_f32 v34, v34, v41, v40
	v_max3_f32 v34, v34, v43, v42
	v_max3_f32 v34, v34, v45, v44
	v_max3_f32 v34, v34, v46, v38
	v_mov_b32_e32 v47, v34
	v_add_u32_e32 v111, 0, v88
	s_add_i32 s26, s26, 1
	v_add_u32_e32 v92, 0x1200, v92
	v_subrev_u32_e32 v91, 32, v91
	v_permlane32_swap_b32_e32 v34, v47
	v_max3_f32 v34, v95, v34, v47
	v_sub_f32_e32 v36, v36, v34
	v_exp_f32_e32 v103, v36
	v_sub_f32_e32 v36, v100, v34
	v_exp_f32_e32 v100, v36
	v_sub_f32_e32 v36, v39, v34
	v_exp_f32_e32 v104, v36
	v_sub_f32_e32 v36, v41, v34
	v_exp_f32_e32 v105, v36
	v_sub_f32_e32 v36, v40, v34
	v_exp_f32_e32 v106, v36
	v_sub_f32_e32 v36, v43, v34
	v_exp_f32_e32 v107, v36
	v_sub_f32_e32 v36, v42, v34
	v_sub_f32_e32 v48, v97, v34
	v_sub_f32_e32 v37, v37, v34
	v_exp_f32_e32 v108, v36
	v_sub_f32_e32 v36, v45, v34
	v_sub_f32_e32 v47, v95, v34
	v_exp_f32_e32 v95, v48
	v_sub_f32_e32 v48, v99, v34
	v_exp_f32_e32 v102, v37
	v_exp_f32_e32 v109, v36
	v_sub_f32_e32 v36, v44, v34
	v_add_u32_e32 v37, 0, v89
	v_sub_f32_e32 v49, v96, v34
	v_exp_f32_e32 v101, v48
	v_exp_f32_e32 v48, v47
	v_exp_f32_e32 v110, v36
	v_sub_f32_e32 v36, v46, v34
	ds_read2_b64 v[44:47], v37 offset1:2
	ds_read2_b64 v[96:99], v111 offset1:2
	v_sub_f32_e32 v35, v35, v34
	v_exp_f32_e32 v49, v49
	v_exp_f32_e32 v35, v35
	v_cvt_pk_bf16_f32 v42, v102, v103
	v_cvt_pk_bf16_f32 v43, v100, v104
	v_pk_mul_f32 v[32:33], v[32:33], v[48:49] op_sel_hi:[1,0]
	v_pk_mul_f32 v[30:31], v[30:31], v[48:49] op_sel_hi:[1,0]
	v_cvt_pk_bf16_f32 v40, v95, v49
	v_cvt_pk_bf16_f32 v41, v101, v35
	v_pk_mul_f32 v[16:17], v[16:17], v[48:49] op_sel_hi:[1,0]
	v_pk_mul_f32 v[14:15], v[14:15], v[48:49] op_sel_hi:[1,0]
	v_pk_mul_f32 v[12:13], v[12:13], v[48:49] op_sel_hi:[1,0]
	v_pk_mul_f32 v[10:11], v[10:11], v[48:49] op_sel_hi:[1,0]
	v_pk_mul_f32 v[8:9], v[8:9], v[48:49] op_sel_hi:[1,0]
	v_pk_mul_f32 v[6:7], v[6:7], v[48:49] op_sel_hi:[1,0]
	v_pk_mul_f32 v[4:5], v[4:5], v[48:49] op_sel_hi:[1,0]
	v_pk_mul_f32 v[2:3], v[2:3], v[48:49] op_sel_hi:[1,0]
	v_pk_mul_f32 v[28:29], v[28:29], v[48:49] op_sel_hi:[1,0]
	v_pk_mul_f32 v[26:27], v[26:27], v[48:49] op_sel_hi:[1,0]
	v_pk_mul_f32 v[24:25], v[24:25], v[48:49] op_sel_hi:[1,0]
	v_pk_mul_f32 v[22:23], v[22:23], v[48:49] op_sel_hi:[1,0]
	v_pk_mul_f32 v[20:21], v[20:21], v[48:49] op_sel_hi:[1,0]
	v_pk_mul_f32 v[18:19], v[18:19], v[48:49] op_sel_hi:[1,0]
	s_waitcnt lgkmcnt(1)
	v_mfma_f32_32x32x16_bf16 v[2:17], v[44:47], v[40:43], v[2:17]
	ds_read2_b64 v[44:47], v37 offset0:4 offset1:6
	v_cvt_pk_bf16_f32 v37, v107, v108
	v_add_u32_e32 v90, 0xffffff80, v90
	v_add_u32_e32 v89, 64, v89
	s_cmp_lt_i32 s26, 4
	v_add_u32_e32 v88, 64, v88
	s_waitcnt lgkmcnt(1)
	v_mfma_f32_32x32x16_bf16 v[18:33], v[96:99], v[40:43], v[18:33]
	ds_read2_b64 v[40:43], v111 offset0:4 offset1:6
	v_exp_f32_e32 v96, v36
	v_sub_f32_e32 v36, v38, v34
	v_exp_f32_e32 v97, v36
	v_cvt_pk_bf16_f32 v36, v105, v106
	v_cvt_pk_bf16_f32 v38, v109, v110
	v_cvt_pk_bf16_f32 v39, v96, v97
	s_waitcnt lgkmcnt(1)
	s_nop 0
	v_mfma_f32_32x32x16_bf16 v[2:17], v[44:47], v[36:39], v[2:17]
	s_waitcnt lgkmcnt(0)
	v_mfma_f32_32x32x16_bf16 v[18:33], v[40:43], v[36:39], v[18:33]
	v_add_f32_e32 v36, 0, v95
	v_add_f32_e32 v36, v49, v36
	v_add_f32_e32 v36, v101, v36
	v_add_f32_e32 v35, v35, v36
	v_add_f32_e32 v35, v102, v35
	v_add_f32_e32 v35, v103, v35
	v_add_f32_e32 v35, v100, v35
	v_add_f32_e32 v35, v104, v35
	v_add_f32_e32 v35, v105, v35
	v_add_f32_e32 v35, v106, v35
	v_add_f32_e32 v35, v107, v35
	v_add_f32_e32 v35, v108, v35
	v_add_f32_e32 v35, v109, v35
	v_add_f32_e32 v35, v110, v35
	v_add_f32_e32 v35, v96, v35
	v_add_f32_e32 v35, v97, v35
	v_fmac_f32_e32 v35, v94, v48
	s_cbranch_scc0 .LBB0_159
	v_mov_b32_e32 v95, v34
	v_mov_b32_e32 v94, v35
	s_branch .LBB0_165

.LBB0_208:
	v_mov_b32_e32 v76, v34
	ds_read_b128 v[34:37], v74
	ds_read_b128 v[78:81], v74 offset:32
	ds_read_b128 v[144:147], v74 offset:64
	ds_read_b128 v[148:151], v74 offset:96
	v_add_u32_e32 v74, 0x1200, v74
	s_waitcnt vmcnt(0) lgkmcnt(3)
	v_mfma_f32_32x32x16_bf16 v[34:49], v[34:37], v[50:53], 0
	s_waitcnt vmcnt(2) lgkmcnt(2)
	v_mfma_f32_32x32x16_bf16 v[34:49], v[78:81], v[54:57], v[34:49]
	s_waitcnt vmcnt(1) lgkmcnt(1)
	v_mfma_f32_32x32x16_bf16 v[34:49], v[144:147], v[58:61], v[34:49]
	s_waitcnt vmcnt(0) lgkmcnt(0)
	v_mfma_f32_32x32x16_bf16 v[34:49], v[148:151], v[62:65], v[34:49]
	s_nop 11
	v_max_f32_e32 v75, v35, v35
	v_max_f32_e32 v78, v34, v34
	v_max_f32_e32 v75, v78, v75
	v_max3_f32 v75, v75, v36, v37
	v_max3_f32 v75, v75, v38, v39
	v_max3_f32 v75, v75, v40, v41
	v_max3_f32 v75, v75, v42, v43
	v_max3_f32 v75, v75, v44, v45
	v_max3_f32 v75, v75, v46, v47
	v_max3_f32 v75, v75, v48, v49
	v_mov_b32_e32 v78, v75
	s_nop 1
	v_permlane32_swap_b32_e32 v75, v78
	v_max3_f32 v75, v77, v75, v78
	v_sub_f32_e32 v34, v34, v75
	v_exp_f32_e32 v86, v34
	v_sub_f32_e32 v34, v35, v75
	v_exp_f32_e32 v87, v34
	v_sub_f32_e32 v34, v36, v75
	v_exp_f32_e32 v88, v34
	v_sub_f32_e32 v34, v37, v75
	v_exp_f32_e32 v89, v34
	v_sub_f32_e32 v34, v38, v75
	v_exp_f32_e32 v90, v34
	v_sub_f32_e32 v34, v39, v75
	v_exp_f32_e32 v91, v34
	v_sub_f32_e32 v34, v40, v75
	v_exp_f32_e32 v92, v34
	v_sub_f32_e32 v34, v41, v75
	v_exp_f32_e32 v93, v34
	v_sub_f32_e32 v34, v42, v75
	v_exp_f32_e32 v94, v34
	v_sub_f32_e32 v34, v43, v75
	v_exp_f32_e32 v43, v34
	v_sub_f32_e32 v34, v44, v75
	v_sub_f32_e32 v77, v77, v75
	v_exp_f32_e32 v95, v34
	v_sub_f32_e32 v34, v45, v75
	v_exp_f32_e32 v96, v34
	v_sub_f32_e32 v34, v46, v75
	v_exp_f32_e32 v42, v77
	v_add_u32_e32 v77, s4, v72
	v_exp_f32_e32 v97, v34
	v_sub_f32_e32 v34, v47, v75
	ds_read2_b64 v[44:47], v77 offset1:2
	ds_read2_b64 v[78:81], v77 offset0:4 offset1:6
	v_exp_f32_e32 v98, v34
	v_sub_f32_e32 v34, v48, v75
	v_exp_f32_e32 v48, v34
	v_sub_f32_e32 v34, v49, v75
	v_exp_f32_e32 v49, v34
	v_cvt_pk_bf16_f32 v34, v86, v87
	v_cvt_pk_bf16_f32 v35, v88, v89
	v_cvt_pk_bf16_f32 v36, v90, v91
	v_cvt_pk_bf16_f32 v37, v92, v93
	v_pk_mul_f32 v[16:17], v[16:17], v[42:43] op_sel_hi:[1,0]
	v_pk_mul_f32 v[14:15], v[14:15], v[42:43] op_sel_hi:[1,0]
	v_pk_mul_f32 v[12:13], v[12:13], v[42:43] op_sel_hi:[1,0]
	v_pk_mul_f32 v[10:11], v[10:11], v[42:43] op_sel_hi:[1,0]
	v_pk_mul_f32 v[8:9], v[8:9], v[42:43] op_sel_hi:[1,0]
	v_pk_mul_f32 v[6:7], v[6:7], v[42:43] op_sel_hi:[1,0]
	v_pk_mul_f32 v[4:5], v[4:5], v[42:43] op_sel_hi:[1,0]
	v_pk_mul_f32 v[2:3], v[2:3], v[42:43] op_sel_hi:[1,0]
	v_add_u32_e32 v77, s4, v71
	v_pk_mul_f32 v[32:33], v[32:33], v[42:43] op_sel_hi:[1,0]
	s_waitcnt lgkmcnt(1)
	v_mfma_f32_32x32x16_bf16 v[2:17], v[44:47], v[34:37], v[2:17]
	ds_read2_b64 v[44:47], v77 offset1:2
	ds_read2_b64 v[82:85], v77 offset0:4 offset1:6
	v_mul_f32_e64 v30, v30, v42
	v_mul_f32_e64 v31, v31, v42
	v_mul_f32_e64 v28, v28, v42
	v_mul_f32_e64 v29, v29, v42
	v_pk_mul_f32 v[26:27], v[26:27], v[42:43] op_sel_hi:[1,0]
	v_pk_mul_f32 v[24:25], v[24:25], v[42:43] op_sel_hi:[1,0]
	v_pk_mul_f32 v[22:23], v[22:23], v[42:43] op_sel_hi:[1,0]
	v_pk_mul_f32 v[20:21], v[20:21], v[42:43] op_sel_hi:[1,0]
	v_pk_mul_f32 v[18:19], v[18:19], v[42:43] op_sel_hi:[1,0]
	v_cvt_pk_bf16_f32 v38, v94, v43
	v_cvt_pk_bf16_f32 v39, v95, v96
	s_waitcnt lgkmcnt(1)
	v_mfma_f32_32x32x16_bf16 v[18:33], v[44:47], v[34:37], v[18:33]
	v_add_f32_e32 v34, 0, v86
	v_add_f32_e32 v34, v87, v34
	v_add_f32_e32 v34, v88, v34
	v_add_f32_e32 v34, v89, v34
	v_add_f32_e32 v34, v90, v34
	v_add_f32_e32 v34, v91, v34
	v_add_f32_e32 v34, v92, v34
	v_add_f32_e32 v34, v93, v34
	v_cvt_pk_bf16_f32 v40, v97, v98
	v_cvt_pk_bf16_f32 v41, v48, v49
	v_add_f32_e32 v34, v94, v34
	v_add_f32_e32 v34, v43, v34
	v_mfma_f32_32x32x16_bf16 v[2:17], v[78:81], v[38:41], v[2:17]
	v_add_f32_e32 v34, v95, v34
	v_add_f32_e32 v34, v96, v34
	v_add_f32_e32 v34, v97, v34
	v_add_f32_e32 v34, v98, v34
	v_add_f32_e32 v34, v48, v34
	v_add_f32_e32 v34, v49, v34
	s_add_i32 s4, s4, 64
	s_waitcnt lgkmcnt(0)
	v_mfma_f32_32x32x16_bf16 v[18:33], v[82:85], v[38:41], v[18:33]
	v_fmac_f32_e32 v34, v76, v42
	s_cmpk_lg_i32 s4, 0x200
	v_mov_b32_e32 v77, v75
	s_cbranch_scc1 .LBB0_208
	ds_bpermute_b32 v35, v70, v34
	s_add_i32 s6, s6, s54
	s_cmpk_lt_i32 s6, 0x200
	s_waitcnt lgkmcnt(0)
	v_add_f32_e32 v34, v34, v35
	v_div_scale_f32 v35, s[4:5], v34, v34, 1.0
	v_rcp_f32_e32 v36, v35
	s_nop 0
	v_fma_f32 v37, -v35, v36, 1.0
	v_fmac_f32_e32 v36, v37, v36
	v_div_scale_f32 v37, vcc, 1.0, v34, 1.0
	v_mul_f32_e32 v38, v37, v36
	v_fma_f32 v39, -v35, v38, v37
	v_fmac_f32_e32 v38, v39, v36
	v_fma_f32 v35, -v35, v38, v37
	v_div_fmas_f32 v35, v35, v36, v38
	v_div_fixup_f32 v34, v35, v34, 1.0
	v_pk_mul_f32 v[2:3], v[2:3], v[34:35] op_sel_hi:[1,0]
	v_pk_mul_f32 v[4:5], v[4:5], v[34:35] op_sel_hi:[1,0]
	v_lshl_add_u64 v[36:37], v[68:69], 0, s[8:9]
	v_cvt_pk_bf16_f32 v2, v2, v3
	v_cvt_pk_bf16_f32 v3, v4, v5
	global_store_dwordx2 v[36:37], v[2:3], off offset:1536
	v_pk_mul_f32 v[2:3], v[18:19], v[34:35] op_sel_hi:[1,0]
	v_pk_mul_f32 v[4:5], v[20:21], v[34:35] op_sel_hi:[1,0]
	v_cvt_pk_bf16_f32 v2, v2, v3
	v_cvt_pk_bf16_f32 v3, v4, v5
	global_store_dwordx2 v[36:37], v[2:3], off offset:1600
	v_pk_mul_f32 v[2:3], v[6:7], v[34:35] op_sel_hi:[1,0]
	v_pk_mul_f32 v[4:5], v[8:9], v[34:35] op_sel_hi:[1,0]
	v_cvt_pk_bf16_f32 v2, v2, v3
	v_cvt_pk_bf16_f32 v3, v4, v5
	global_store_dwordx2 v[36:37], v[2:3], off offset:1552
	v_pk_mul_f32 v[2:3], v[22:23], v[34:35] op_sel_hi:[1,0]
	v_pk_mul_f32 v[4:5], v[24:25], v[34:35] op_sel_hi:[1,0]
	v_cvt_pk_bf16_f32 v2, v2, v3
	v_cvt_pk_bf16_f32 v3, v4, v5
	global_store_dwordx2 v[36:37], v[2:3], off offset:1616
	v_pk_mul_f32 v[2:3], v[10:11], v[34:35] op_sel_hi:[1,0]
	v_pk_mul_f32 v[4:5], v[12:13], v[34:35] op_sel_hi:[1,0]
	v_cvt_pk_bf16_f32 v2, v2, v3
	v_cvt_pk_bf16_f32 v3, v4, v5
	global_store_dwordx2 v[36:37], v[2:3], off offset:1568
	v_pk_mul_f32 v[2:3], v[26:27], v[34:35] op_sel_hi:[1,0]
	v_pk_mul_f32 v[4:5], v[28:29], v[34:35] op_sel_hi:[1,0]
	v_cvt_pk_bf16_f32 v2, v2, v3
	v_cvt_pk_bf16_f32 v3, v4, v5
	global_store_dwordx2 v[36:37], v[2:3], off offset:1632
	v_pk_mul_f32 v[2:3], v[14:15], v[34:35] op_sel_hi:[1,0]
	v_pk_mul_f32 v[4:5], v[16:17], v[34:35] op_sel_hi:[1,0]
	v_cvt_pk_bf16_f32 v2, v2, v3
	v_cvt_pk_bf16_f32 v3, v4, v5
	global_store_dwordx2 v[36:37], v[2:3], off offset:1584
	v_pk_mul_f32 v[2:3], v[30:31], v[34:35] op_sel_hi:[1,0]
	v_pk_mul_f32 v[4:5], v[32:33], v[34:35] op_sel_hi:[1,0]
	v_cvt_pk_bf16_f32 v2, v2, v3
	v_cvt_pk_bf16_f32 v3, v4, v5
	global_store_dwordx2 v[36:37], v[2:3], off offset:1648
	s_cbranch_scc1 .LBB0_207

.LBB0_356:
	v_mov_b32_e32 v76, v34
	ds_read_b128 v[34:37], v74
	ds_read_b128 v[78:81], v74 offset:32
	ds_read_b128 v[144:147], v74 offset:64
	ds_read_b128 v[148:151], v74 offset:96
	v_add_u32_e32 v74, 0x1200, v74
	s_waitcnt vmcnt(3) lgkmcnt(3)
	v_mfma_f32_32x32x16_bf16 v[34:49], v[34:37], v[50:53], 0
	s_waitcnt vmcnt(2) lgkmcnt(2)
	v_mfma_f32_32x32x16_bf16 v[34:49], v[78:81], v[54:57], v[34:49]
	s_waitcnt vmcnt(1) lgkmcnt(1)
	v_mfma_f32_32x32x16_bf16 v[34:49], v[144:147], v[58:61], v[34:49]
	s_waitcnt vmcnt(0) lgkmcnt(0)
	v_mfma_f32_32x32x16_bf16 v[34:49], v[148:151], v[62:65], v[34:49]
	s_nop 11
	v_max_f32_e32 v75, v35, v35
	v_max_f32_e32 v78, v34, v34
	v_max_f32_e32 v75, v78, v75
	v_max3_f32 v75, v75, v36, v37
	v_max3_f32 v75, v75, v38, v39
	v_max3_f32 v75, v75, v40, v41
	v_max3_f32 v75, v75, v42, v43
	v_max3_f32 v75, v75, v44, v45
	v_max3_f32 v75, v75, v46, v47
	v_max3_f32 v75, v75, v48, v49
	v_mov_b32_e32 v78, v75
	s_nop 1
	v_permlane32_swap_b32_e32 v75, v78
	v_max3_f32 v75, v77, v75, v78
	v_sub_f32_e32 v34, v34, v75
	v_exp_f32_e32 v86, v34
	v_sub_f32_e32 v34, v35, v75
	v_exp_f32_e32 v87, v34
	v_sub_f32_e32 v34, v36, v75
	v_exp_f32_e32 v88, v34
	v_sub_f32_e32 v34, v37, v75
	v_exp_f32_e32 v89, v34
	v_sub_f32_e32 v34, v38, v75
	v_exp_f32_e32 v90, v34
	v_sub_f32_e32 v34, v39, v75
	v_exp_f32_e32 v91, v34
	v_sub_f32_e32 v34, v40, v75
	v_exp_f32_e32 v92, v34
	v_sub_f32_e32 v34, v41, v75
	v_exp_f32_e32 v93, v34
	v_sub_f32_e32 v34, v42, v75
	v_exp_f32_e32 v94, v34
	v_sub_f32_e32 v34, v43, v75
	v_exp_f32_e32 v43, v34
	v_sub_f32_e32 v34, v44, v75
	v_sub_f32_e32 v77, v77, v75
	v_exp_f32_e32 v95, v34
	v_sub_f32_e32 v34, v45, v75
	v_exp_f32_e32 v96, v34
	v_sub_f32_e32 v34, v46, v75
	v_exp_f32_e32 v42, v77
	v_add_u32_e32 v77, s4, v72
	v_exp_f32_e32 v97, v34
	v_sub_f32_e32 v34, v47, v75
	ds_read2_b64 v[44:47], v77 offset1:2
	ds_read2_b64 v[78:81], v77 offset0:4 offset1:6
	v_exp_f32_e32 v98, v34
	v_sub_f32_e32 v34, v48, v75
	v_exp_f32_e32 v48, v34
	v_sub_f32_e32 v34, v49, v75
	v_exp_f32_e32 v49, v34
	v_cvt_pk_bf16_f32 v34, v86, v87
	v_cvt_pk_bf16_f32 v35, v88, v89
	v_cvt_pk_bf16_f32 v36, v90, v91
	v_cvt_pk_bf16_f32 v37, v92, v93
	v_pk_mul_f32 v[16:17], v[16:17], v[42:43] op_sel_hi:[1,0]
	v_pk_mul_f32 v[14:15], v[14:15], v[42:43] op_sel_hi:[1,0]
	v_pk_mul_f32 v[12:13], v[12:13], v[42:43] op_sel_hi:[1,0]
	v_pk_mul_f32 v[10:11], v[10:11], v[42:43] op_sel_hi:[1,0]
	v_pk_mul_f32 v[8:9], v[8:9], v[42:43] op_sel_hi:[1,0]
	v_pk_mul_f32 v[6:7], v[6:7], v[42:43] op_sel_hi:[1,0]
	v_pk_mul_f32 v[4:5], v[4:5], v[42:43] op_sel_hi:[1,0]
	v_pk_mul_f32 v[2:3], v[2:3], v[42:43] op_sel_hi:[1,0]
	v_add_u32_e32 v77, s4, v71
	v_pk_mul_f32 v[32:33], v[32:33], v[42:43] op_sel_hi:[1,0]
	s_waitcnt lgkmcnt(1)
	v_mfma_f32_32x32x16_bf16 v[2:17], v[44:47], v[34:37], v[2:17]
	ds_read2_b64 v[44:47], v77 offset1:2
	ds_read2_b64 v[82:85], v77 offset0:4 offset1:6
	v_mul_f32_e64 v30, v30, v42
	v_mul_f32_e64 v31, v31, v42
	v_mul_f32_e64 v28, v28, v42
	v_mul_f32_e64 v29, v29, v42
	v_pk_mul_f32 v[26:27], v[26:27], v[42:43] op_sel_hi:[1,0]
	v_pk_mul_f32 v[24:25], v[24:25], v[42:43] op_sel_hi:[1,0]
	v_pk_mul_f32 v[22:23], v[22:23], v[42:43] op_sel_hi:[1,0]
	v_pk_mul_f32 v[20:21], v[20:21], v[42:43] op_sel_hi:[1,0]
	v_pk_mul_f32 v[18:19], v[18:19], v[42:43] op_sel_hi:[1,0]
	v_cvt_pk_bf16_f32 v38, v94, v43
	v_cvt_pk_bf16_f32 v39, v95, v96
	s_waitcnt lgkmcnt(1)
	v_mfma_f32_32x32x16_bf16 v[18:33], v[44:47], v[34:37], v[18:33]
	v_add_f32_e32 v34, 0, v86
	v_add_f32_e32 v34, v87, v34
	v_add_f32_e32 v34, v88, v34
	v_add_f32_e32 v34, v89, v34
	v_add_f32_e32 v34, v90, v34
	v_add_f32_e32 v34, v91, v34
	v_add_f32_e32 v34, v92, v34
	v_add_f32_e32 v34, v93, v34
	v_cvt_pk_bf16_f32 v40, v97, v98
	v_cvt_pk_bf16_f32 v41, v48, v49
	v_add_f32_e32 v34, v94, v34
	v_add_f32_e32 v34, v43, v34
	v_mfma_f32_32x32x16_bf16 v[2:17], v[78:81], v[38:41], v[2:17]
	v_add_f32_e32 v34, v95, v34
	v_add_f32_e32 v34, v96, v34
	v_add_f32_e32 v34, v97, v34
	v_add_f32_e32 v34, v98, v34
	v_add_f32_e32 v34, v48, v34
	v_add_f32_e32 v34, v49, v34
	s_add_i32 s4, s4, 64
	s_waitcnt lgkmcnt(0)
	v_mfma_f32_32x32x16_bf16 v[18:33], v[82:85], v[38:41], v[18:33]
	v_fmac_f32_e32 v34, v76, v42
	s_cmpk_lg_i32 s4, 0x200
	v_mov_b32_e32 v77, v75
	s_cbranch_scc1 .LBB0_356
	ds_bpermute_b32 v35, v70, v34
	s_lshl_b64 s[4:5], s[8:9], 11
	s_add_i32 s6, s6, s54
	s_cmpk_lt_i32 s6, 0x200
	s_waitcnt lgkmcnt(0)
	v_add_f32_e32 v34, v34, v35
	v_div_scale_f32 v35, s[8:9], v34, v34, 1.0
	v_rcp_f32_e32 v36, v35
	s_nop 0
	v_fma_f32 v37, -v35, v36, 1.0
	v_fmac_f32_e32 v36, v37, v36
	v_div_scale_f32 v37, vcc, 1.0, v34, 1.0
	v_mul_f32_e32 v38, v37, v36
	v_fma_f32 v39, -v35, v38, v37
	v_fmac_f32_e32 v38, v39, v36
	v_fma_f32 v35, -v35, v38, v37
	v_div_fmas_f32 v35, v35, v36, v38
	v_div_fixup_f32 v34, v35, v34, 1.0
	v_pk_mul_f32 v[2:3], v[2:3], v[34:35] op_sel_hi:[1,0]
	v_pk_mul_f32 v[4:5], v[4:5], v[34:35] op_sel_hi:[1,0]
	v_lshl_add_u64 v[36:37], v[68:69], 0, s[4:5]
	v_cvt_pk_bf16_f32 v2, v2, v3
	v_cvt_pk_bf16_f32 v3, v4, v5
	global_store_dwordx2 v[36:37], v[2:3], off offset:1536
	v_pk_mul_f32 v[2:3], v[18:19], v[34:35] op_sel_hi:[1,0]
	v_pk_mul_f32 v[4:5], v[20:21], v[34:35] op_sel_hi:[1,0]
	v_cvt_pk_bf16_f32 v2, v2, v3
	v_cvt_pk_bf16_f32 v3, v4, v5
	global_store_dwordx2 v[36:37], v[2:3], off offset:1600
	v_pk_mul_f32 v[2:3], v[6:7], v[34:35] op_sel_hi:[1,0]
	v_pk_mul_f32 v[4:5], v[8:9], v[34:35] op_sel_hi:[1,0]
	v_cvt_pk_bf16_f32 v2, v2, v3
	v_cvt_pk_bf16_f32 v3, v4, v5
	global_store_dwordx2 v[36:37], v[2:3], off offset:1552
	v_pk_mul_f32 v[2:3], v[22:23], v[34:35] op_sel_hi:[1,0]
	v_pk_mul_f32 v[4:5], v[24:25], v[34:35] op_sel_hi:[1,0]
	v_cvt_pk_bf16_f32 v2, v2, v3
	v_cvt_pk_bf16_f32 v3, v4, v5
	global_store_dwordx2 v[36:37], v[2:3], off offset:1616
	v_pk_mul_f32 v[2:3], v[10:11], v[34:35] op_sel_hi:[1,0]
	v_pk_mul_f32 v[4:5], v[12:13], v[34:35] op_sel_hi:[1,0]
	v_cvt_pk_bf16_f32 v2, v2, v3
	v_cvt_pk_bf16_f32 v3, v4, v5
	global_store_dwordx2 v[36:37], v[2:3], off offset:1568
	v_pk_mul_f32 v[2:3], v[26:27], v[34:35] op_sel_hi:[1,0]
	v_pk_mul_f32 v[4:5], v[28:29], v[34:35] op_sel_hi:[1,0]
	v_cvt_pk_bf16_f32 v2, v2, v3
	v_cvt_pk_bf16_f32 v3, v4, v5
	global_store_dwordx2 v[36:37], v[2:3], off offset:1632
	v_pk_mul_f32 v[2:3], v[14:15], v[34:35] op_sel_hi:[1,0]
	v_pk_mul_f32 v[4:5], v[16:17], v[34:35] op_sel_hi:[1,0]
	v_cvt_pk_bf16_f32 v2, v2, v3
	v_cvt_pk_bf16_f32 v3, v4, v5
	global_store_dwordx2 v[36:37], v[2:3], off offset:1584
	v_pk_mul_f32 v[2:3], v[30:31], v[34:35] op_sel_hi:[1,0]
	v_pk_mul_f32 v[4:5], v[32:33], v[34:35] op_sel_hi:[1,0]
	v_cvt_pk_bf16_f32 v2, v2, v3
	v_cvt_pk_bf16_f32 v3, v4, v5
	global_store_dwordx2 v[36:37], v[2:3], off offset:1648
	s_cbranch_scc1 .LBB0_355
